# v15 with the pipelined attention loop (exp/sum of the next tile's first score block done in the PV phase)
# speedup vs baseline: 1.0201x; 1.0170x over previous
.LBB0_1038:
	s_or_b64 exec, exec, s[4:5]
	v_and_b32_e32 v0, 0x60, v26
	s_movk_i32 s4, 0x90
	v_lshlrev_b32_e32 v2, 3, v32
	v_mad_u32_u24 v207, v203, s4, 0
	v_mad_u64_u32 v[0:1], s[4:5], v28, s4, v[0:1]
	v_and_or_b32 v0, v2, 8, v0
	v_lshlrev_b32_e32 v1, 6, v203
	v_add_u32_e32 v208, 0, v0
	v_add3_u32 v204, v207, v1, v184
	v_add_u32_e32 v1, 0, v4
	v_add_u32_e32 v205, 0x9800, v208
	s_waitcnt vmcnt(3)
	ds_write_b128 v1, v[8:11] offset:13312
	s_waitcnt vmcnt(2)
	ds_write2_b64 v205, v[16:17], v[18:19] offset0:128 offset1:130
	s_waitcnt lgkmcnt(0)
	s_barrier
	ds_read_b128 v[0:3], v204
	ds_read_b128 v[4:7], v204 offset:32
	ds_read_b128 v[8:11], v204 offset:6656
	ds_read_b128 v[12:15], v204 offset:6688
	ds_read_b128 v[16:19], v204 offset:64
	ds_read_b128 v[28:31], v204 offset:96
	ds_read_b128 v[64:67], v204 offset:6720
	ds_read_b128 v[68:71], v204 offset:6752
	ds_read_b128 v[72:75], v204 offset:128
	ds_read_b128 v[76:79], v204 offset:160
	ds_read_b128 v[80:83], v204 offset:6784
	ds_read_b128 v[84:87], v204 offset:6816
	s_mov_b32 s91, 2
	s_lshl_b32 s87, s6, 2
	s_waitcnt lgkmcnt(11)
	v_mfma_f32_32x32x16_bf16 v[48:63], v[0:3], v[100:103], 0
	s_mov_b32 s79, 0
	s_waitcnt lgkmcnt(9)
	v_mfma_f32_32x32x16_bf16 v[32:47], v[8:11], v[100:103], 0
	v_mfma_f32_32x32x16_bf16 v[48:63], v[4:7], v[104:107], v[48:63]
	s_waitcnt lgkmcnt(8)
	v_mfma_f32_32x32x16_bf16 v[32:47], v[12:15], v[104:107], v[32:47]
	s_waitcnt lgkmcnt(7)
	v_mfma_f32_32x32x16_bf16 v[48:63], v[16:19], v[108:111], v[48:63]
	s_waitcnt lgkmcnt(5)
	v_mfma_f32_32x32x16_bf16 v[32:47], v[64:67], v[108:111], v[32:47]
	v_mfma_f32_32x32x16_bf16 v[48:63], v[28:31], v[112:115], v[48:63]
	s_waitcnt lgkmcnt(4)
	v_mfma_f32_32x32x16_bf16 v[32:47], v[68:71], v[112:115], v[32:47]
	s_waitcnt lgkmcnt(3)
	v_mfma_f32_32x32x16_bf16 v[48:63], v[72:75], v[116:119], v[48:63]
	s_waitcnt lgkmcnt(1)
	v_mfma_f32_32x32x16_bf16 v[32:47], v[80:83], v[116:119], v[32:47]
	v_mfma_f32_32x32x16_bf16 v[48:63], v[76:79], v[120:123], v[48:63]
	s_waitcnt lgkmcnt(0)
	v_mfma_f32_32x32x16_bf16 v[32:47], v[84:87], v[120:123], v[32:47]
	ds_read_b128 v[172:175], v204 offset:13312
	ds_read_b128 v[152:155], v204 offset:13344
	ds_read_b128 v[180:183], v204 offset:19968
	ds_read_b128 v[164:167], v204 offset:20000
	ds_read_b128 v[156:159], v204 offset:13376
	ds_read_b128 v[140:143], v204 offset:13408
	ds_read_b128 v[176:179], v204 offset:20032
	ds_read_b128 v[160:163], v204 offset:20064
	ds_read_b128 v[148:151], v204 offset:13440
	ds_read_b128 v[136:139], v204 offset:13472
	ds_read_b128 v[168:171], v204 offset:20096
	ds_read_b128 v[144:147], v204 offset:20128
	s_add_u32 s4, s60, 0x100
	v_lshl_add_u64 v[0:1], s[60:61], 0, v[24:25]
	v_mov_b32_e32 v27, v97
	s_addc_u32 s5, 0, 0
	v_lshl_add_u64 v[190:191], v[0:1], 0, v[26:27]
	v_lshl_add_u64 v[0:1], s[4:5], 0, v[24:25]
	v_mov_b32_e32 v199, 0
	v_lshl_add_u64 v[188:189], s[96:97], 0, v[20:21]
	v_lshl_add_u64 v[186:187], s[96:97], 0, v[22:23]
	v_lshl_add_u64 v[98:99], v[0:1], 0, v[26:27]
	s_add_u32 s98, s94, 0x12209000
	s_addc_u32 s99, s95, 0
	s_add_u32 s100, s94, 0x11200000
	s_addc_u32 s101, s95, 0

	v_exp_f32_e32 v48, v48
	v_exp_f32_e32 v49, v49
	v_exp_f32_e32 v50, v50
	v_add_f32_e32 v195, v48, v49
	v_exp_f32_e32 v51, v51
	v_add_f32_e32 v195, v50, v195
	v_exp_f32_e32 v52, v52
	v_add_f32_e32 v195, v51, v195
	v_exp_f32_e32 v53, v53
	v_add_f32_e32 v195, v52, v195
	v_exp_f32_e32 v54, v54
	v_add_f32_e32 v195, v53, v195
	v_exp_f32_e32 v55, v55
	v_add_f32_e32 v195, v54, v195
	v_exp_f32_e32 v56, v56
	v_add_f32_e32 v195, v55, v195
	v_exp_f32_e32 v57, v57
	v_add_f32_e32 v195, v56, v195
	v_exp_f32_e32 v58, v58
	v_add_f32_e32 v195, v57, v195
	v_exp_f32_e32 v59, v59
	v_add_f32_e32 v195, v58, v195
	v_exp_f32_e32 v60, v60
	v_add_f32_e32 v195, v59, v195
	v_exp_f32_e32 v61, v61
	v_add_f32_e32 v195, v60, v195
	v_exp_f32_e32 v62, v62
	v_add_f32_e32 v195, v61, v195
	v_exp_f32_e32 v63, v63
	v_add_f32_e32 v195, v62, v195
	v_add_f32_e32 v195, v63, v195
	s_movk_i32 s93, 0xbf
	v_mov_b32_e32 v0, 0
	v_mov_b32_e32 v1, v199
	v_mov_b32_e32 v2, v199
	v_mov_b32_e32 v3, v199
	v_mov_b32_e32 v4, v199
	v_mov_b32_e32 v5, v199
	v_mov_b32_e32 v6, v199
	v_mov_b32_e32 v7, v199
	v_mov_b32_e32 v8, v199
	v_mov_b32_e32 v9, v199
	v_mov_b32_e32 v10, v199
	v_mov_b32_e32 v11, v199
	v_mov_b32_e32 v12, v199
	v_mov_b32_e32 v13, v199
	v_mov_b32_e32 v14, v199
	v_mov_b32_e32 v15, v199
	v_mov_b32_e32 v16, 0
	v_mov_b32_e32 v17, v199
	v_mov_b32_e32 v18, v199
	v_mov_b32_e32 v19, v199
	v_mov_b32_e32 v20, v199
	v_mov_b32_e32 v21, v199
	v_mov_b32_e32 v22, v199
	v_mov_b32_e32 v23, v199
	v_mov_b32_e32 v24, v199
	v_mov_b32_e32 v25, v199
	v_mov_b32_e32 v26, v199
	v_mov_b32_e32 v27, v199
	v_mov_b32_e32 v28, v199
	v_mov_b32_e32 v29, v199
	v_mov_b32_e32 v30, v199
	v_mov_b32_e32 v31, v199
.LBB0_1039:
	s_waitcnt lgkmcnt(11)
	v_mfma_f32_32x32x16_bf16 v[64:79], v[172:175], v[100:103], 0
	v_exp_f32_e32 v32, v32
	v_exp_f32_e32 v33, v33
	v_exp_f32_e32 v34, v34
	s_waitcnt lgkmcnt(9)
	v_mfma_f32_32x32x16_bf16 v[80:95], v[180:183], v[100:103], 0
	v_add_f32_e32 v251, v32, v33
	v_cvt_pk_bf16_f32 v48, v48, v49
	v_exp_f32_e32 v35, v35
	v_add_f32_e32 v251, v34, v251
	v_mfma_f32_32x32x16_bf16 v[64:79], v[152:155], v[104:107], v[64:79]
	v_exp_f32_e32 v36, v36
	v_add_f32_e32 v251, v35, v251
	v_cvt_pk_bf16_f32 v49, v50, v51
	v_exp_f32_e32 v37, v37
	s_waitcnt lgkmcnt(8)
	v_mfma_f32_32x32x16_bf16 v[80:95], v[164:167], v[104:107], v[80:95]
	v_add_f32_e32 v251, v36, v251
	v_exp_f32_e32 v38, v38
	v_add_f32_e32 v251, v37, v251
	v_cvt_pk_bf16_f32 v50, v52, v53
	s_waitcnt lgkmcnt(7)
	v_mfma_f32_32x32x16_bf16 v[64:79], v[156:159], v[108:111], v[64:79]
	v_exp_f32_e32 v39, v39
	v_add_f32_e32 v251, v38, v251
	v_exp_f32_e32 v40, v40
	s_mul_i32 s6, s91, 0x3400
	s_add_i32 s7, s6, 0

	v_add_u32_e32 v253, s7, v96
	s_waitcnt vmcnt(1)
	ds_write_b128 v253, v[128:131]
	s_and_saveexec_b64 s[4:5], s[2:3]
	v_add_u32_e32 v253, s7, v185
	ds_write_b128 v253, v[124:127]
	s_or_b64 exec, exec, s[4:5]
	v_lshl_add_u64 v[200:201], s[100:101], 0, v[190:191]

	v_add_u32_e32 v206, 0xc000, v208
	v_lshl_add_u64 v[128:129], s[98:99], 0, v[188:189]
	s_nop 0
	global_load_dwordx4 v[128:131], v[128:129], off
	s_waitcnt vmcnt(1)
	ds_write2_b64 v206, v[132:133], v[134:135] offset1:2

	s_and_saveexec_b64 s[4:5], s[2:3]
	s_cbranch_execz .LatA_h0
	v_lshl_add_u64 v[124:125], s[98:99], 0, v[186:187]
	s_nop 0
	global_load_dwordx4 v[124:127], v[124:125], off
.LatA_h0:
	s_or_b64 exec, exec, s[4:5]
	global_load_dwordx4 v[132:135], v[200:201], off offset:256

	s_waitcnt lgkmcnt(7)
	v_mfma_f32_32x32x16_bf16 v[80:95], v[176:179], v[108:111], v[80:95]
	v_add_f32_e32 v251, v39, v251
	v_cvt_pk_bf16_f32 v51, v54, v55
	v_exp_f32_e32 v41, v41
	v_add_f32_e32 v251, v40, v251
	v_mfma_f32_32x32x16_bf16 v[64:79], v[140:143], v[112:115], v[64:79]
	v_exp_f32_e32 v42, v42
	v_add_f32_e32 v251, v41, v251
	v_cvt_pk_bf16_f32 v52, v56, v57
	v_exp_f32_e32 v43, v43
	s_waitcnt lgkmcnt(6)
	v_mfma_f32_32x32x16_bf16 v[80:95], v[160:163], v[112:115], v[80:95]
	v_add_f32_e32 v251, v42, v251
	v_exp_f32_e32 v44, v44
	v_add_f32_e32 v251, v43, v251
	v_cvt_pk_bf16_f32 v53, v58, v59
	s_waitcnt lgkmcnt(5)
	v_mfma_f32_32x32x16_bf16 v[64:79], v[148:151], v[116:119], v[64:79]
	v_exp_f32_e32 v45, v45
	v_add_f32_e32 v251, v44, v251
	v_exp_f32_e32 v46, v46
	v_add_f32_e32 v251, v45, v251
	v_add_u32_e32 v198, v207, v184
	ds_read_b128 v[210:213], v198 offset:44544
	ds_read_b128 v[214:217], v198 offset:39936
	ds_read_b128 v[218:221], v198 offset:39968
	ds_read_b128 v[222:225], v198 offset:44576
	ds_read_b128 v[226:229], v198 offset:40000
	ds_read_b128 v[230:233], v198 offset:44608
	ds_read_b128 v[234:237], v198 offset:40032
	ds_read_b128 v[238:241], v198 offset:44640
	s_waitcnt lgkmcnt(11)
	v_mfma_f32_32x32x16_bf16 v[80:95], v[168:171], v[116:119], v[80:95]
	v_cvt_pk_bf16_f32 v54, v60, v61
	v_exp_f32_e32 v47, v47
	v_add_f32_e32 v251, v46, v251
	v_add_f32_e32 v251, v47, v251
	v_mfma_f32_32x32x16_bf16 v[64:79], v[136:139], v[120:123], v[64:79]
	v_cvt_pk_bf16_f32 v55, v62, v63
	v_cvt_pk_bf16_f32 v32, v32, v33
	v_cvt_pk_bf16_f32 v33, v34, v35
	v_cvt_pk_bf16_f32 v34, v36, v37
	v_cvt_pk_bf16_f32 v35, v38, v39
	v_cvt_pk_bf16_f32 v36, v40, v41
	s_waitcnt lgkmcnt(10)
	v_mfma_f32_32x32x16_bf16 v[80:95], v[144:147], v[120:123], v[80:95]
	v_cvt_pk_bf16_f32 v37, v42, v43
	v_cvt_pk_bf16_f32 v38, v44, v45
	v_cvt_pk_bf16_f32 v39, v46, v47
	v_add_f32_e32 v195, v195, v251
	v_add_f32_e32 v199, v199, v195
	s_waitcnt lgkmcnt(0)
	s_barrier

	v_add_u32_e32 v197, s6, v204
	s_setprio 1
	v_mfma_f32_32x32x16_bf16 v[0:15], v[48:51], v[210:213], v[0:15]
	ds_read_b128 v[172:175], v197
	ds_read_b128 v[152:155], v197 offset:32
	v_mfma_f32_32x32x16_bf16 v[0:15], v[52:55], v[222:225], v[0:15]
	ds_read_b128 v[180:183], v197 offset:6656
	ds_read_b128 v[164:167], v197 offset:6688
	v_mfma_f32_32x32x16_bf16 v[0:15], v[32:35], v[230:233], v[0:15]
	ds_read_b128 v[156:159], v197 offset:64
	ds_read_b128 v[140:143], v197 offset:96
	v_exp_f32_e32 v64, v64
	v_exp_f32_e32 v65, v65
	v_exp_f32_e32 v66, v66
	v_add_f32_e32 v195, v64, v65
	v_mfma_f32_32x32x16_bf16 v[0:15], v[36:39], v[238:241], v[0:15]
	s_setprio 0
	ds_read_b128 v[176:179], v197 offset:6720
	ds_read_b128 v[160:163], v197 offset:6752
	v_exp_f32_e32 v67, v67
	v_add_f32_e32 v195, v66, v195
	v_exp_f32_e32 v68, v68
	v_add_f32_e32 v195, v67, v195
	v_exp_f32_e32 v69, v69
	v_add_f32_e32 v195, v68, v195
	v_mfma_f32_32x32x16_bf16 v[16:31], v[48:51], v[214:217], v[16:31]
	ds_read_b128 v[148:151], v197 offset:128
	ds_read_b128 v[136:139], v197 offset:160
	v_exp_f32_e32 v70, v70
	v_add_f32_e32 v195, v69, v195
	v_exp_f32_e32 v71, v71
	v_add_f32_e32 v195, v70, v195
	v_exp_f32_e32 v72, v72
	v_mfma_f32_32x32x16_bf16 v[16:31], v[52:55], v[218:221], v[16:31]
	ds_read_b128 v[168:171], v197 offset:6784
	ds_read_b128 v[144:147], v197 offset:6816
	v_add_f32_e32 v195, v71, v195
	v_exp_f32_e32 v73, v73
	v_add_f32_e32 v195, v72, v195
	v_exp_f32_e32 v74, v74
	v_add_f32_e32 v195, v73, v195
	v_mfma_f32_32x32x16_bf16 v[16:31], v[32:35], v[226:229], v[16:31]
	v_exp_f32_e32 v75, v75
	v_add_f32_e32 v195, v74, v195
	v_exp_f32_e32 v76, v76
	v_add_f32_e32 v195, v75, v195
	v_exp_f32_e32 v77, v77
	v_mfma_f32_32x32x16_bf16 v[16:31], v[36:39], v[234:237], v[16:31]
	v_add_f32_e32 v195, v76, v195
	v_exp_f32_e32 v78, v78
	v_add_f32_e32 v195, v77, v195
	v_exp_f32_e32 v79, v79
	v_add_f32_e32 v195, v78, v195
	v_add_f32_e32 v195, v79, v195
	s_waitcnt lgkmcnt(11)
	v_mfma_f32_32x32x16_bf16 v[48:63], v[172:175], v[100:103], 0
	v_exp_f32_e32 v80, v80
	v_exp_f32_e32 v81, v81
	v_exp_f32_e32 v82, v82
	s_waitcnt lgkmcnt(9)
	v_mfma_f32_32x32x16_bf16 v[32:47], v[180:183], v[100:103], 0
	v_add_f32_e32 v251, v80, v81
	v_cvt_pk_bf16_f32 v64, v64, v65
	v_exp_f32_e32 v83, v83
	v_add_f32_e32 v251, v82, v251
	v_mfma_f32_32x32x16_bf16 v[48:63], v[152:155], v[104:107], v[48:63]
	v_exp_f32_e32 v84, v84
	v_add_f32_e32 v251, v83, v251
	v_cvt_pk_bf16_f32 v65, v66, v67
	v_exp_f32_e32 v85, v85
	s_waitcnt lgkmcnt(8)
	v_mfma_f32_32x32x16_bf16 v[32:47], v[164:167], v[104:107], v[32:47]
	v_add_f32_e32 v251, v84, v251
	v_exp_f32_e32 v86, v86
	v_add_f32_e32 v251, v85, v251
	v_cvt_pk_bf16_f32 v66, v68, v69
	s_waitcnt lgkmcnt(7)
	v_mfma_f32_32x32x16_bf16 v[48:63], v[156:159], v[108:111], v[48:63]
	v_exp_f32_e32 v87, v87
	v_add_f32_e32 v251, v86, v251
	v_exp_f32_e32 v88, v88
	s_add_i32 s4, s91, 1
	s_cmp_lg_u32 s91, 2
	s_cselect_b32 s74, s4, 0
	s_mul_i32 s6, s74, 0x3400
	s_add_i32 s7, s6, 0
	s_add_u32 s98, s98, 0x3000
	s_addc_u32 s99, s99, 0

	v_add_u32_e32 v253, s7, v96
	s_waitcnt vmcnt(1)
	ds_write_b128 v253, v[128:131]
	s_and_saveexec_b64 s[4:5], s[2:3]
	v_add_u32_e32 v253, s7, v185
	ds_write_b128 v253, v[124:127]
	s_or_b64 exec, exec, s[4:5]
	v_lshl_add_u64 v[200:201], s[100:101], 0, v[190:191]

	s_waitcnt vmcnt(0)
	ds_write2_b64 v205, v[132:133], v[134:135] offset0:128 offset1:130
	v_lshl_add_u64 v[128:129], s[98:99], 0, v[188:189]
	s_nop 0
	global_load_dwordx4 v[128:131], v[128:129], off

	s_and_saveexec_b64 s[4:5], s[2:3]
	s_cbranch_execz .LatA_h1
	v_lshl_add_u64 v[124:125], s[98:99], 0, v[186:187]
	s_nop 0
	global_load_dwordx4 v[124:127], v[124:125], off
.LatA_h1:
	s_or_b64 exec, exec, s[4:5]
	global_load_dwordx4 v[132:135], v[200:201], off offset:384

	s_sub_u32 s98, s98, 0x3000
	s_subb_u32 s99, s99, 0

	s_waitcnt lgkmcnt(7)
	v_mfma_f32_32x32x16_bf16 v[32:47], v[176:179], v[108:111], v[32:47]
	v_add_f32_e32 v251, v87, v251
	v_cvt_pk_bf16_f32 v67, v70, v71
	v_exp_f32_e32 v89, v89
	v_add_f32_e32 v251, v88, v251
	v_mfma_f32_32x32x16_bf16 v[48:63], v[140:143], v[112:115], v[48:63]
	v_exp_f32_e32 v90, v90
	v_add_f32_e32 v251, v89, v251
	v_cvt_pk_bf16_f32 v68, v72, v73
	v_exp_f32_e32 v91, v91
	s_waitcnt lgkmcnt(6)
	v_mfma_f32_32x32x16_bf16 v[32:47], v[160:163], v[112:115], v[32:47]
	v_add_f32_e32 v251, v90, v251
	v_exp_f32_e32 v92, v92
	v_add_f32_e32 v251, v91, v251
	v_cvt_pk_bf16_f32 v69, v74, v75
	s_waitcnt lgkmcnt(5)
	v_mfma_f32_32x32x16_bf16 v[48:63], v[148:151], v[116:119], v[48:63]
	v_exp_f32_e32 v93, v93
	v_add_f32_e32 v251, v92, v251
	v_exp_f32_e32 v94, v94
	v_add_f32_e32 v251, v93, v251
	v_add_u32_e32 v198, v207, v184
	ds_read_b128 v[210:213], v198 offset:53760
	ds_read_b128 v[214:217], v198 offset:49152
	ds_read_b128 v[218:221], v198 offset:49184
	ds_read_b128 v[222:225], v198 offset:53792
	ds_read_b128 v[226:229], v198 offset:49216
	ds_read_b128 v[230:233], v198 offset:53824
	ds_read_b128 v[234:237], v198 offset:49248
	ds_read_b128 v[238:241], v198 offset:53856
	s_waitcnt lgkmcnt(11)
	v_mfma_f32_32x32x16_bf16 v[32:47], v[168:171], v[116:119], v[32:47]
	v_cvt_pk_bf16_f32 v70, v76, v77
	v_exp_f32_e32 v95, v95
	v_add_f32_e32 v251, v94, v251
	v_add_f32_e32 v251, v95, v251
	v_mfma_f32_32x32x16_bf16 v[48:63], v[136:139], v[120:123], v[48:63]
	v_cvt_pk_bf16_f32 v71, v78, v79
	v_cvt_pk_bf16_f32 v80, v80, v81
	v_cvt_pk_bf16_f32 v81, v82, v83
	v_cvt_pk_bf16_f32 v82, v84, v85
	v_cvt_pk_bf16_f32 v83, v86, v87
	v_cvt_pk_bf16_f32 v84, v88, v89
	s_waitcnt lgkmcnt(10)
	v_mfma_f32_32x32x16_bf16 v[32:47], v[144:147], v[120:123], v[32:47]
	v_cvt_pk_bf16_f32 v85, v90, v91
	v_cvt_pk_bf16_f32 v86, v92, v93
	v_cvt_pk_bf16_f32 v87, v94, v95
	v_add_f32_e32 v195, v195, v251
	v_add_f32_e32 v199, v199, v195
	s_add_i32 s92, s79, 2
	s_waitcnt lgkmcnt(0)
	s_barrier

	s_cmp_ge_u32 s92, s87
	s_cbranch_scc1 .LatA_yplain

	v_add_u32_e32 v197, s6, v204
	s_setprio 1
	v_mfma_f32_32x32x16_bf16 v[0:15], v[64:67], v[210:213], v[0:15]
	ds_read_b128 v[172:175], v197
	ds_read_b128 v[152:155], v197 offset:32
	v_mfma_f32_32x32x16_bf16 v[0:15], v[68:71], v[222:225], v[0:15]
	ds_read_b128 v[180:183], v197 offset:6656
	ds_read_b128 v[164:167], v197 offset:6688
	v_mfma_f32_32x32x16_bf16 v[0:15], v[80:83], v[230:233], v[0:15]
	ds_read_b128 v[156:159], v197 offset:64
	ds_read_b128 v[140:143], v197 offset:96
	v_exp_f32_e32 v48, v48
	v_exp_f32_e32 v49, v49
	v_exp_f32_e32 v50, v50
	v_add_f32_e32 v195, v48, v49
	v_mfma_f32_32x32x16_bf16 v[0:15], v[84:87], v[238:241], v[0:15]
	s_setprio 0
	ds_read_b128 v[176:179], v197 offset:6720
	ds_read_b128 v[160:163], v197 offset:6752
	v_exp_f32_e32 v51, v51
	v_add_f32_e32 v195, v50, v195
	v_exp_f32_e32 v52, v52
	v_add_f32_e32 v195, v51, v195
	v_exp_f32_e32 v53, v53
	v_add_f32_e32 v195, v52, v195
	v_mfma_f32_32x32x16_bf16 v[16:31], v[64:67], v[214:217], v[16:31]
	ds_read_b128 v[148:151], v197 offset:128
	ds_read_b128 v[136:139], v197 offset:160
	v_exp_f32_e32 v54, v54
	v_add_f32_e32 v195, v53, v195
	v_exp_f32_e32 v55, v55
	v_add_f32_e32 v195, v54, v195
	v_exp_f32_e32 v56, v56
	v_mfma_f32_32x32x16_bf16 v[16:31], v[68:71], v[218:221], v[16:31]
	ds_read_b128 v[168:171], v197 offset:6784
	ds_read_b128 v[144:147], v197 offset:6816
	v_add_f32_e32 v195, v55, v195
	v_exp_f32_e32 v57, v57
	v_add_f32_e32 v195, v56, v195
	v_exp_f32_e32 v58, v58
	v_add_f32_e32 v195, v57, v195
	v_mfma_f32_32x32x16_bf16 v[16:31], v[80:83], v[226:229], v[16:31]
	v_exp_f32_e32 v59, v59
	v_add_f32_e32 v195, v58, v195
	v_exp_f32_e32 v60, v60
	v_add_f32_e32 v195, v59, v195
	v_exp_f32_e32 v61, v61
	v_mfma_f32_32x32x16_bf16 v[16:31], v[84:87], v[234:237], v[16:31]
	v_add_f32_e32 v195, v60, v195
	v_exp_f32_e32 v62, v62
	v_add_f32_e32 v195, v61, v195
	v_exp_f32_e32 v63, v63
	v_add_f32_e32 v195, v62, v195
	v_add_f32_e32 v195, v63, v195
	s_branch .LatA_ctl
.LatA_yplain:
	v_add_u32_e32 v197, s6, v204
	s_setprio 1
	v_mfma_f32_32x32x16_bf16 v[0:15], v[64:67], v[210:213], v[0:15]
	ds_read_b128 v[172:175], v197
	ds_read_b128 v[152:155], v197 offset:32
	v_mfma_f32_32x32x16_bf16 v[0:15], v[68:71], v[222:225], v[0:15]
	ds_read_b128 v[180:183], v197 offset:6656
	ds_read_b128 v[164:167], v197 offset:6688
	v_mfma_f32_32x32x16_bf16 v[0:15], v[80:83], v[230:233], v[0:15]
	ds_read_b128 v[156:159], v197 offset:64
	ds_read_b128 v[140:143], v197 offset:96
	v_mfma_f32_32x32x16_bf16 v[0:15], v[84:87], v[238:241], v[0:15]
	s_setprio 0
	ds_read_b128 v[176:179], v197 offset:6720
	ds_read_b128 v[160:163], v197 offset:6752
	v_mfma_f32_32x32x16_bf16 v[16:31], v[64:67], v[214:217], v[16:31]
	ds_read_b128 v[148:151], v197 offset:128
	ds_read_b128 v[136:139], v197 offset:160
	v_mfma_f32_32x32x16_bf16 v[16:31], v[68:71], v[218:221], v[16:31]
	ds_read_b128 v[168:171], v197 offset:6784
	ds_read_b128 v[144:147], v197 offset:6816
	v_mfma_f32_32x32x16_bf16 v[16:31], v[80:83], v[226:229], v[16:31]
	v_mfma_f32_32x32x16_bf16 v[16:31], v[84:87], v[234:237], v[16:31]
.LatA_ctl:
	s_add_i32 s4, s74, 1
	s_cmp_lg_u32 s74, 2
	s_cselect_b32 s91, s4, 0
	s_add_i32 s4, s93, 0x80
	v_lshl_add_u64 v[188:189], v[188:189], 0, s[82:83]
	v_lshl_add_u64 v[186:187], v[186:187], 0, s[82:83]
	v_lshl_add_u64 v[190:191], v[190:191], 0, s[66:67]
	s_cmp_ge_u32 s92, s87
	v_lshl_add_u64 v[192:193], v[98:99], 0, s[66:67]
	s_cbranch_scc1 .LBB0_1049
	v_mov_b64_e32 v[98:99], v[192:193]
	s_mov_b32 s93, s4
	s_mov_b32 s79, s92
	s_branch .LBB0_1039


.LBB0_1103:
	s_or_b64 exec, exec, s[4:5]
	v_and_b32_e32 v2, 0x60, v190
	s_movk_i32 s4, 0x90
	v_lshlrev_b32_e32 v1, 3, v24
	v_mad_u32_u24 v208, v207, s4, 0
	v_mad_u64_u32 v[2:3], s[4:5], v20, s4, v[2:3]
	v_and_or_b32 v1, v1, 8, v2
	v_lshlrev_b32_e32 v2, 6, v207
	v_add_u32_e32 v210, 0, v1
	v_add3_u32 v209, v208, v2, v184
	v_add_u32_e32 v0, 0, v0
	v_add_u32_e32 v211, 0x9800, v210
	s_waitcnt vmcnt(3)
	ds_write_b128 v0, v[4:7] offset:13312
	s_waitcnt vmcnt(2)
	ds_write2_b64 v211, v[8:9], v[10:11] offset0:128 offset1:130
	s_waitcnt lgkmcnt(0)
	s_barrier
	ds_read_b128 v[0:3], v209
	ds_read_b128 v[4:7], v209 offset:32
	ds_read_b128 v[8:11], v209 offset:6656
	ds_read_b128 v[12:15], v209 offset:6688
	ds_read_b128 v[16:19], v209 offset:64
	ds_read_b128 v[20:23], v209 offset:96
	ds_read_b128 v[24:27], v209 offset:6720
	ds_read_b128 v[28:31], v209 offset:6752
	ds_read_b128 v[64:67], v209 offset:128
	ds_read_b128 v[68:71], v209 offset:160
	ds_read_b128 v[72:75], v209 offset:6784
	ds_read_b128 v[76:79], v209 offset:6816
	s_mov_b32 s90, 2
	s_lshl_b32 s69, s68, 2
	s_mov_b32 s40, 0
	s_cmp_eq_u32 s68, 0
	s_waitcnt lgkmcnt(11)
	v_mfma_f32_32x32x16_bf16 v[48:63], v[0:3], v[100:103], 0
	s_waitcnt lgkmcnt(9)
	v_mfma_f32_32x32x16_bf16 v[32:47], v[8:11], v[100:103], 0
	v_mfma_f32_32x32x16_bf16 v[48:63], v[4:7], v[104:107], v[48:63]
	s_waitcnt lgkmcnt(8)
	v_mfma_f32_32x32x16_bf16 v[32:47], v[12:15], v[104:107], v[32:47]
	s_waitcnt lgkmcnt(7)
	v_mfma_f32_32x32x16_bf16 v[48:63], v[16:19], v[108:111], v[48:63]
	s_waitcnt lgkmcnt(5)
	v_mfma_f32_32x32x16_bf16 v[32:47], v[24:27], v[108:111], v[32:47]
	v_mfma_f32_32x32x16_bf16 v[48:63], v[20:23], v[112:115], v[48:63]
	s_waitcnt lgkmcnt(4)
	v_mfma_f32_32x32x16_bf16 v[32:47], v[28:31], v[112:115], v[32:47]
	s_waitcnt lgkmcnt(3)
	v_mfma_f32_32x32x16_bf16 v[48:63], v[64:67], v[116:119], v[48:63]
	s_waitcnt lgkmcnt(1)
	v_mfma_f32_32x32x16_bf16 v[32:47], v[72:75], v[116:119], v[32:47]
	v_mfma_f32_32x32x16_bf16 v[48:63], v[68:71], v[120:123], v[48:63]
	s_waitcnt lgkmcnt(0)
	v_mfma_f32_32x32x16_bf16 v[32:47], v[76:79], v[120:123], v[32:47]
	s_cbranch_scc1 .LBB0_1114
	ds_read_b128 v[172:175], v209 offset:13312
	ds_read_b128 v[152:155], v209 offset:13344
	ds_read_b128 v[180:183], v209 offset:19968
	ds_read_b128 v[164:167], v209 offset:20000
	ds_read_b128 v[156:159], v209 offset:13376
	ds_read_b128 v[140:143], v209 offset:13408
	ds_read_b128 v[176:179], v209 offset:20032
	ds_read_b128 v[160:163], v209 offset:20064
	ds_read_b128 v[148:151], v209 offset:13440
	ds_read_b128 v[136:139], v209 offset:13472
	ds_read_b128 v[168:171], v209 offset:20096
	ds_read_b128 v[144:147], v209 offset:20128
	v_lshl_add_u64 v[0:1], s[60:61], 0, v[192:193]
	v_mov_b32_e32 v191, v97
	v_mov_b32_e32 v198, 0
	v_lshl_add_u64 v[98:99], s[96:97], 0, v[186:187]
	v_lshl_add_u64 v[202:203], s[96:97], 0, v[188:189]
	v_lshl_add_u64 v[204:205], v[0:1], 0, v[190:191]
	s_add_u32 s98, s94, 0x12209000
	s_addc_u32 s99, s95, 0
	s_add_u32 s100, s94, 0x11200000
	s_addc_u32 s101, s95, 0

	v_exp_f32_e32 v48, v48
	v_exp_f32_e32 v49, v49
	v_exp_f32_e32 v50, v50
	v_add_f32_e32 v195, v48, v49
	v_exp_f32_e32 v51, v51
	v_add_f32_e32 v195, v50, v195
	v_exp_f32_e32 v52, v52
	v_add_f32_e32 v195, v51, v195
	v_exp_f32_e32 v53, v53
	v_add_f32_e32 v195, v52, v195
	v_exp_f32_e32 v54, v54
	v_add_f32_e32 v195, v53, v195
	v_exp_f32_e32 v55, v55
	v_add_f32_e32 v195, v54, v195
	v_exp_f32_e32 v56, v56
	v_add_f32_e32 v195, v55, v195
	v_exp_f32_e32 v57, v57
	v_add_f32_e32 v195, v56, v195
	v_exp_f32_e32 v58, v58
	v_add_f32_e32 v195, v57, v195
	v_exp_f32_e32 v59, v59
	v_add_f32_e32 v195, v58, v195
	v_exp_f32_e32 v60, v60
	v_add_f32_e32 v195, v59, v195
	v_exp_f32_e32 v61, v61
	v_add_f32_e32 v195, v60, v195
	v_exp_f32_e32 v62, v62
	v_add_f32_e32 v195, v61, v195
	v_exp_f32_e32 v63, v63
	v_add_f32_e32 v195, v62, v195
	v_add_f32_e32 v195, v63, v195
	v_mov_b32_e32 v0, 0
	v_mov_b32_e32 v1, v198
	v_mov_b32_e32 v2, v198
	v_mov_b32_e32 v3, v198
	v_mov_b32_e32 v4, v198
	v_mov_b32_e32 v5, v198
	v_mov_b32_e32 v6, v198
	v_mov_b32_e32 v7, v198
	v_mov_b32_e32 v8, v198
	v_mov_b32_e32 v9, v198
	v_mov_b32_e32 v10, v198
	v_mov_b32_e32 v11, v198
	v_mov_b32_e32 v12, v198
	v_mov_b32_e32 v13, v198
	v_mov_b32_e32 v14, v198
	v_mov_b32_e32 v15, v198
	v_mov_b32_e32 v16, 0
	v_mov_b32_e32 v17, v198
	v_mov_b32_e32 v18, v198
	v_mov_b32_e32 v19, v198
	v_mov_b32_e32 v20, v198
	v_mov_b32_e32 v21, v198
	v_mov_b32_e32 v22, v198
	v_mov_b32_e32 v23, v198
	v_mov_b32_e32 v24, v198
	v_mov_b32_e32 v25, v198
	v_mov_b32_e32 v26, v198
	v_mov_b32_e32 v27, v198
	v_mov_b32_e32 v28, v198
	v_mov_b32_e32 v29, v198
	v_mov_b32_e32 v30, v198
	v_mov_b32_e32 v31, v198
	s_mov_b32 s41, 0x2c000
	s_branch .LBB0_1106
.LBB0_1106:
	s_waitcnt lgkmcnt(11)
	v_mfma_f32_32x32x16_bf16 v[64:79], v[172:175], v[100:103], 0
	v_exp_f32_e32 v32, v32
	v_exp_f32_e32 v33, v33
	v_exp_f32_e32 v34, v34
	s_waitcnt lgkmcnt(9)
	v_mfma_f32_32x32x16_bf16 v[80:95], v[180:183], v[100:103], 0
	v_add_f32_e32 v251, v32, v33
	v_cvt_pk_bf16_f32 v48, v48, v49
	v_exp_f32_e32 v35, v35
	v_add_f32_e32 v251, v34, v251
	v_mfma_f32_32x32x16_bf16 v[64:79], v[152:155], v[104:107], v[64:79]
	v_exp_f32_e32 v36, v36
	v_add_f32_e32 v251, v35, v251
	v_cvt_pk_bf16_f32 v49, v50, v51
	v_exp_f32_e32 v37, v37
	s_waitcnt lgkmcnt(8)
	v_mfma_f32_32x32x16_bf16 v[80:95], v[164:167], v[104:107], v[80:95]
	v_add_f32_e32 v251, v36, v251
	v_exp_f32_e32 v38, v38
	v_add_f32_e32 v251, v37, v251
	v_cvt_pk_bf16_f32 v50, v52, v53
	s_waitcnt lgkmcnt(7)
	v_mfma_f32_32x32x16_bf16 v[64:79], v[156:159], v[108:111], v[64:79]
	v_exp_f32_e32 v39, v39
	v_add_f32_e32 v251, v38, v251
	v_exp_f32_e32 v40, v40
	s_mul_i32 s6, s90, 0x3400
	s_add_i32 s7, s6, 0

	v_add_u32_e32 v253, s7, v96
	s_waitcnt vmcnt(1)
	ds_write_b128 v253, v[128:131]
	s_and_saveexec_b64 s[4:5], s[2:3]
	v_add_u32_e32 v253, s7, v185
	ds_write_b128 v253, v[124:127]
	s_or_b64 exec, exec, s[4:5]
	v_lshl_add_u64 v[200:201], s[100:101], 0, v[204:205]

	v_add_u32_e32 v254, 0xc000, v210
	v_lshl_add_u64 v[128:129], s[98:99], 0, v[98:99]
	s_nop 0
	global_load_dwordx4 v[128:131], v[128:129], off
	s_waitcnt vmcnt(1)
	ds_write2_b64 v254, v[132:133], v[134:135] offset1:2

	s_and_saveexec_b64 s[4:5], s[2:3]
	s_cbranch_execz .LatB_h0
	v_lshl_add_u64 v[124:125], s[98:99], 0, v[202:203]
	s_nop 0
	global_load_dwordx4 v[124:127], v[124:125], off
.LatB_h0:
	s_or_b64 exec, exec, s[4:5]
	global_load_dwordx4 v[132:135], v[200:201], off offset:256

	s_waitcnt lgkmcnt(7)
	v_mfma_f32_32x32x16_bf16 v[80:95], v[176:179], v[108:111], v[80:95]
	v_add_f32_e32 v251, v39, v251
	v_cvt_pk_bf16_f32 v51, v54, v55
	v_exp_f32_e32 v41, v41
	v_add_f32_e32 v251, v40, v251
	v_mfma_f32_32x32x16_bf16 v[64:79], v[140:143], v[112:115], v[64:79]
	v_exp_f32_e32 v42, v42
	v_add_f32_e32 v251, v41, v251
	v_cvt_pk_bf16_f32 v52, v56, v57
	v_exp_f32_e32 v43, v43
	s_waitcnt lgkmcnt(6)
	v_mfma_f32_32x32x16_bf16 v[80:95], v[160:163], v[112:115], v[80:95]
	v_add_f32_e32 v251, v42, v251
	v_exp_f32_e32 v44, v44
	v_add_f32_e32 v251, v43, v251
	v_cvt_pk_bf16_f32 v53, v58, v59
	s_waitcnt lgkmcnt(5)
	v_mfma_f32_32x32x16_bf16 v[64:79], v[148:151], v[116:119], v[64:79]
	v_exp_f32_e32 v45, v45
	v_add_f32_e32 v251, v44, v251
	v_exp_f32_e32 v46, v46
	v_add_f32_e32 v251, v45, v251
	v_add_u32_e32 v196, v208, v184
	ds_read_b128 v[212:215], v196 offset:44544
	ds_read_b128 v[216:219], v196 offset:39936
	ds_read_b128 v[220:223], v196 offset:39968
	ds_read_b128 v[224:227], v196 offset:44576
	ds_read_b128 v[228:231], v196 offset:40000
	ds_read_b128 v[232:235], v196 offset:44608
	ds_read_b128 v[236:239], v196 offset:40032
	ds_read_b128 v[240:243], v196 offset:44640
	s_waitcnt lgkmcnt(11)
	v_mfma_f32_32x32x16_bf16 v[80:95], v[168:171], v[116:119], v[80:95]
	v_cvt_pk_bf16_f32 v54, v60, v61
	v_exp_f32_e32 v47, v47
	v_add_f32_e32 v251, v46, v251
	v_add_f32_e32 v251, v47, v251
	v_mfma_f32_32x32x16_bf16 v[64:79], v[136:139], v[120:123], v[64:79]
	v_cvt_pk_bf16_f32 v55, v62, v63
	v_cvt_pk_bf16_f32 v32, v32, v33
	v_cvt_pk_bf16_f32 v33, v34, v35
	v_cvt_pk_bf16_f32 v34, v36, v37
	v_cvt_pk_bf16_f32 v35, v38, v39
	v_cvt_pk_bf16_f32 v36, v40, v41
	s_waitcnt lgkmcnt(10)
	v_mfma_f32_32x32x16_bf16 v[80:95], v[144:147], v[120:123], v[80:95]
	v_cvt_pk_bf16_f32 v37, v42, v43
	v_cvt_pk_bf16_f32 v38, v44, v45
	v_cvt_pk_bf16_f32 v39, v46, v47
	v_add_f32_e32 v195, v195, v251
	v_add_f32_e32 v198, v198, v195
	s_waitcnt lgkmcnt(0)
	s_barrier

	v_add_u32_e32 v197, s6, v209
	s_setprio 1
	v_mfma_f32_32x32x16_bf16 v[0:15], v[48:51], v[212:215], v[0:15]
	ds_read_b128 v[172:175], v197
	ds_read_b128 v[152:155], v197 offset:32
	v_mfma_f32_32x32x16_bf16 v[0:15], v[52:55], v[224:227], v[0:15]
	ds_read_b128 v[180:183], v197 offset:6656
	ds_read_b128 v[164:167], v197 offset:6688
	v_mfma_f32_32x32x16_bf16 v[0:15], v[32:35], v[232:235], v[0:15]
	ds_read_b128 v[156:159], v197 offset:64
	ds_read_b128 v[140:143], v197 offset:96
	v_exp_f32_e32 v64, v64
	v_exp_f32_e32 v65, v65
	v_exp_f32_e32 v66, v66
	v_add_f32_e32 v195, v64, v65
	v_mfma_f32_32x32x16_bf16 v[0:15], v[36:39], v[240:243], v[0:15]
	s_setprio 0
	ds_read_b128 v[176:179], v197 offset:6720
	ds_read_b128 v[160:163], v197 offset:6752
	v_exp_f32_e32 v67, v67
	v_add_f32_e32 v195, v66, v195
	v_exp_f32_e32 v68, v68
	v_add_f32_e32 v195, v67, v195
	v_exp_f32_e32 v69, v69
	v_add_f32_e32 v195, v68, v195
	v_mfma_f32_32x32x16_bf16 v[16:31], v[48:51], v[216:219], v[16:31]
	ds_read_b128 v[148:151], v197 offset:128
	ds_read_b128 v[136:139], v197 offset:160
	v_exp_f32_e32 v70, v70
	v_add_f32_e32 v195, v69, v195
	v_exp_f32_e32 v71, v71
	v_add_f32_e32 v195, v70, v195
	v_exp_f32_e32 v72, v72
	v_mfma_f32_32x32x16_bf16 v[16:31], v[52:55], v[220:223], v[16:31]
	ds_read_b128 v[168:171], v197 offset:6784
	ds_read_b128 v[144:147], v197 offset:6816
	v_add_f32_e32 v195, v71, v195
	v_exp_f32_e32 v73, v73
	v_add_f32_e32 v195, v72, v195
	v_exp_f32_e32 v74, v74
	v_add_f32_e32 v195, v73, v195
	v_mfma_f32_32x32x16_bf16 v[16:31], v[32:35], v[228:231], v[16:31]
	v_exp_f32_e32 v75, v75
	v_add_f32_e32 v195, v74, v195
	v_exp_f32_e32 v76, v76
	v_add_f32_e32 v195, v75, v195
	v_exp_f32_e32 v77, v77
	v_mfma_f32_32x32x16_bf16 v[16:31], v[36:39], v[236:239], v[16:31]
	v_add_f32_e32 v195, v76, v195
	v_exp_f32_e32 v78, v78
	v_add_f32_e32 v195, v77, v195
	v_exp_f32_e32 v79, v79
	v_add_f32_e32 v195, v78, v195
	v_add_f32_e32 v195, v79, v195
	s_waitcnt lgkmcnt(11)
	v_mfma_f32_32x32x16_bf16 v[48:63], v[172:175], v[100:103], 0
	v_exp_f32_e32 v80, v80
	v_exp_f32_e32 v81, v81
	v_exp_f32_e32 v82, v82
	s_waitcnt lgkmcnt(9)
	v_mfma_f32_32x32x16_bf16 v[32:47], v[180:183], v[100:103], 0
	v_add_f32_e32 v251, v80, v81
	v_cvt_pk_bf16_f32 v64, v64, v65
	v_exp_f32_e32 v83, v83
	v_add_f32_e32 v251, v82, v251
	v_mfma_f32_32x32x16_bf16 v[48:63], v[152:155], v[104:107], v[48:63]
	v_exp_f32_e32 v84, v84
	v_add_f32_e32 v251, v83, v251
	v_cvt_pk_bf16_f32 v65, v66, v67
	v_exp_f32_e32 v85, v85
	s_waitcnt lgkmcnt(8)
	v_mfma_f32_32x32x16_bf16 v[32:47], v[164:167], v[104:107], v[32:47]
	v_add_f32_e32 v251, v84, v251
	v_exp_f32_e32 v86, v86
	v_add_f32_e32 v251, v85, v251
	v_cvt_pk_bf16_f32 v66, v68, v69
	s_waitcnt lgkmcnt(7)
	v_mfma_f32_32x32x16_bf16 v[48:63], v[156:159], v[108:111], v[48:63]
	v_exp_f32_e32 v87, v87
	v_add_f32_e32 v251, v86, v251
	v_exp_f32_e32 v88, v88
	s_add_i32 s4, s90, 1
	s_cmp_lg_u32 s90, 2
	s_cselect_b32 s68, s4, 0
	s_mul_i32 s6, s68, 0x3400
	s_add_i32 s7, s6, 0
	s_add_u32 s98, s98, 0x3000
	s_addc_u32 s99, s99, 0

	v_add_u32_e32 v253, s7, v96
	s_waitcnt vmcnt(1)
	ds_write_b128 v253, v[128:131]
	s_and_saveexec_b64 s[4:5], s[2:3]
	v_add_u32_e32 v253, s7, v185
	ds_write_b128 v253, v[124:127]
	s_or_b64 exec, exec, s[4:5]
	v_lshl_add_u64 v[200:201], s[100:101], 0, v[204:205]

	s_waitcnt vmcnt(0)
	ds_write2_b64 v211, v[132:133], v[134:135] offset0:128 offset1:130
	v_lshl_add_u64 v[128:129], s[98:99], 0, v[98:99]
	s_nop 0
	global_load_dwordx4 v[128:131], v[128:129], off

	s_and_saveexec_b64 s[4:5], s[2:3]
	s_cbranch_execz .LatB_h1
	v_lshl_add_u64 v[124:125], s[98:99], 0, v[202:203]
	s_nop 0
	global_load_dwordx4 v[124:127], v[124:125], off
.LatB_h1:
	s_or_b64 exec, exec, s[4:5]
	global_load_dwordx4 v[132:135], v[200:201], off offset:384

	s_sub_u32 s98, s98, 0x3000
	s_subb_u32 s99, s99, 0

	s_waitcnt lgkmcnt(7)
	v_mfma_f32_32x32x16_bf16 v[32:47], v[176:179], v[108:111], v[32:47]
	v_add_f32_e32 v251, v87, v251
	v_cvt_pk_bf16_f32 v67, v70, v71
	v_exp_f32_e32 v89, v89
	v_add_f32_e32 v251, v88, v251
	v_mfma_f32_32x32x16_bf16 v[48:63], v[140:143], v[112:115], v[48:63]
	v_exp_f32_e32 v90, v90
	v_add_f32_e32 v251, v89, v251
	v_cvt_pk_bf16_f32 v68, v72, v73
	v_exp_f32_e32 v91, v91
	s_waitcnt lgkmcnt(6)
	v_mfma_f32_32x32x16_bf16 v[32:47], v[160:163], v[112:115], v[32:47]
	v_add_f32_e32 v251, v90, v251
	v_exp_f32_e32 v92, v92
	v_add_f32_e32 v251, v91, v251
	v_cvt_pk_bf16_f32 v69, v74, v75
	s_waitcnt lgkmcnt(5)
	v_mfma_f32_32x32x16_bf16 v[48:63], v[148:151], v[116:119], v[48:63]
	v_exp_f32_e32 v93, v93
	v_add_f32_e32 v251, v92, v251
	v_exp_f32_e32 v94, v94
	v_add_f32_e32 v251, v93, v251
	v_add_u32_e32 v196, v208, v184
	ds_read_b128 v[212:215], v196 offset:53760
	ds_read_b128 v[216:219], v196 offset:49152
	ds_read_b128 v[220:223], v196 offset:49184
	ds_read_b128 v[224:227], v196 offset:53792
	ds_read_b128 v[228:231], v196 offset:49216
	ds_read_b128 v[232:235], v196 offset:53824
	ds_read_b128 v[236:239], v196 offset:49248
	ds_read_b128 v[240:243], v196 offset:53856
	s_waitcnt lgkmcnt(11)
	v_mfma_f32_32x32x16_bf16 v[32:47], v[168:171], v[116:119], v[32:47]
	v_cvt_pk_bf16_f32 v70, v76, v77
	v_exp_f32_e32 v95, v95
	v_add_f32_e32 v251, v94, v251
	v_add_f32_e32 v251, v95, v251
	v_mfma_f32_32x32x16_bf16 v[48:63], v[136:139], v[120:123], v[48:63]
	v_cvt_pk_bf16_f32 v71, v78, v79
	v_cvt_pk_bf16_f32 v80, v80, v81
	v_cvt_pk_bf16_f32 v81, v82, v83
	v_cvt_pk_bf16_f32 v82, v84, v85
	v_cvt_pk_bf16_f32 v83, v86, v87
	v_cvt_pk_bf16_f32 v84, v88, v89
	s_waitcnt lgkmcnt(10)
	v_mfma_f32_32x32x16_bf16 v[32:47], v[144:147], v[120:123], v[32:47]
	v_cvt_pk_bf16_f32 v85, v90, v91
	v_cvt_pk_bf16_f32 v86, v92, v93
	v_cvt_pk_bf16_f32 v87, v94, v95
	v_add_f32_e32 v195, v195, v251
	v_add_f32_e32 v198, v198, v195
	s_add_i32 s40, s40, 2
	s_waitcnt lgkmcnt(0)
	s_barrier

	s_cmp_ge_u32 s40, s69
	s_cbranch_scc1 .LatB_yplain

	v_add_u32_e32 v197, s6, v209
	s_setprio 1
	v_mfma_f32_32x32x16_bf16 v[0:15], v[64:67], v[212:215], v[0:15]
	ds_read_b128 v[172:175], v197
	ds_read_b128 v[152:155], v197 offset:32
	v_mfma_f32_32x32x16_bf16 v[0:15], v[68:71], v[224:227], v[0:15]
	ds_read_b128 v[180:183], v197 offset:6656
	ds_read_b128 v[164:167], v197 offset:6688
	v_mfma_f32_32x32x16_bf16 v[0:15], v[80:83], v[232:235], v[0:15]
	ds_read_b128 v[156:159], v197 offset:64
	ds_read_b128 v[140:143], v197 offset:96
	v_exp_f32_e32 v48, v48
	v_exp_f32_e32 v49, v49
	v_exp_f32_e32 v50, v50
	v_add_f32_e32 v195, v48, v49
	v_mfma_f32_32x32x16_bf16 v[0:15], v[84:87], v[240:243], v[0:15]
	s_setprio 0
	ds_read_b128 v[176:179], v197 offset:6720
	ds_read_b128 v[160:163], v197 offset:6752
	v_exp_f32_e32 v51, v51
	v_add_f32_e32 v195, v50, v195
	v_exp_f32_e32 v52, v52
	v_add_f32_e32 v195, v51, v195
	v_exp_f32_e32 v53, v53
	v_add_f32_e32 v195, v52, v195
	v_mfma_f32_32x32x16_bf16 v[16:31], v[64:67], v[216:219], v[16:31]
	ds_read_b128 v[148:151], v197 offset:128
	ds_read_b128 v[136:139], v197 offset:160
	v_exp_f32_e32 v54, v54
	v_add_f32_e32 v195, v53, v195
	v_exp_f32_e32 v55, v55
	v_add_f32_e32 v195, v54, v195
	v_exp_f32_e32 v56, v56
	v_mfma_f32_32x32x16_bf16 v[16:31], v[68:71], v[220:223], v[16:31]
	ds_read_b128 v[168:171], v197 offset:6784
	ds_read_b128 v[144:147], v197 offset:6816
	v_add_f32_e32 v195, v55, v195
	v_exp_f32_e32 v57, v57
	v_add_f32_e32 v195, v56, v195
	v_exp_f32_e32 v58, v58
	v_add_f32_e32 v195, v57, v195
	v_mfma_f32_32x32x16_bf16 v[16:31], v[80:83], v[228:231], v[16:31]
	v_exp_f32_e32 v59, v59
	v_add_f32_e32 v195, v58, v195
	v_exp_f32_e32 v60, v60
	v_add_f32_e32 v195, v59, v195
	v_exp_f32_e32 v61, v61
	v_mfma_f32_32x32x16_bf16 v[16:31], v[84:87], v[236:239], v[16:31]
	v_add_f32_e32 v195, v60, v195
	v_exp_f32_e32 v62, v62
	v_add_f32_e32 v195, v61, v195
	v_exp_f32_e32 v63, v63
	v_add_f32_e32 v195, v62, v195
	v_add_f32_e32 v195, v63, v195
	s_branch .LatB_ctl
.LatB_yplain:
	v_add_u32_e32 v197, s6, v209
	s_setprio 1
	v_mfma_f32_32x32x16_bf16 v[0:15], v[64:67], v[212:215], v[0:15]
	ds_read_b128 v[172:175], v197
	ds_read_b128 v[152:155], v197 offset:32
	v_mfma_f32_32x32x16_bf16 v[0:15], v[68:71], v[224:227], v[0:15]
	ds_read_b128 v[180:183], v197 offset:6656
	ds_read_b128 v[164:167], v197 offset:6688
	v_mfma_f32_32x32x16_bf16 v[0:15], v[80:83], v[232:235], v[0:15]
	ds_read_b128 v[156:159], v197 offset:64
	ds_read_b128 v[140:143], v197 offset:96
	v_mfma_f32_32x32x16_bf16 v[0:15], v[84:87], v[240:243], v[0:15]
	s_setprio 0
	ds_read_b128 v[176:179], v197 offset:6720
	ds_read_b128 v[160:163], v197 offset:6752
	v_mfma_f32_32x32x16_bf16 v[16:31], v[64:67], v[216:219], v[16:31]
	ds_read_b128 v[148:151], v197 offset:128
	ds_read_b128 v[136:139], v197 offset:160
	v_mfma_f32_32x32x16_bf16 v[16:31], v[68:71], v[220:223], v[16:31]
	ds_read_b128 v[168:171], v197 offset:6784
	ds_read_b128 v[144:147], v197 offset:6816
	v_mfma_f32_32x32x16_bf16 v[16:31], v[80:83], v[228:231], v[16:31]
	v_mfma_f32_32x32x16_bf16 v[16:31], v[84:87], v[236:239], v[16:31]
.LatB_ctl:
	s_add_i32 s4, s68, 1
	s_cmp_lg_u32 s68, 2
	s_cselect_b32 s90, s4, 0
	v_lshl_add_u64 v[98:99], v[98:99], 0, s[82:83]
	v_lshl_add_u64 v[202:203], v[202:203], 0, s[82:83]
	s_cmp_ge_u32 s40, s69
	v_lshl_add_u64 v[204:205], v[204:205], 0, s[66:67]
	s_cbranch_scc1 .LBB0_1115
	s_branch .LBB0_1106

